# RWKV solve LDS-operand prefetch; A1 rows+conv weights preloaded per item; A1 items of one 64-token output line group mapped to one XCD (A2 mapping unchanged)
# speedup vs baseline: 1.0224x; 1.0107x over previous
; #define PH(k) for (int _r = 0; _r < NREP(k); ++_r) if (fresh_ctx(c, p, p_arg.ws))
; #define LASTREP(k) (_r + 1 == NREP(k))
; __global__ __launch_bounds__(512) void fwd_megakernel(P p_arg) {
;     ...
;         for (int it0 = c.bid; it0 < 256; it0 += c.G) {
;             const int xq = it0 & 7, yq = it0 >> 3; const int it = (yq < 24) ? ((xq * 4 + yq / 6) * 6 + yq % 6) : (192 + (yq - 24) * 8 + xq);
;             if (it < 192) { PH(4) mlstm_item(p, c, seg, it, LASTREP(4)); }
.LBB0_336:
	s_or_b64 exec, exec, s[2:3]
	s_mov_b32 s45, s90
	s_cmpk_gt_i32 s45, 0xff
	s_waitcnt lgkmcnt(0)
	s_barrier
	s_cbranch_scc1 .LBB0_405
	v_readlane_b32 s2, v255, 31
	s_cmp_lg_u32 s2, 0
	s_cselect_b64 s[4:5], -1, 0
	s_lshl_b32 s2, s2, 9
	v_writelane_b32 v255, s4, 43
	s_add_i32 s94, s2, 0xfffffe00
	s_ashr_i32 s95, s94, 31
	v_writelane_b32 v255, s5, 44
	s_branch .LBB0_340
